# v70_a1_bcum_dot_on_f32_mfma_32x32x2
# speedup vs baseline: 1.0051x; 1.0039x over previous
; #define LAS __attribute__((address_space(3)))
; __device__ __forceinline__ void gla_bcum(KArgs a, int tid, int t0, int h, LAS float* segtot, LAS float* glrs, float (&bc)[32], float& tot) {
;     ...
;     const float* glr = (const float*)(a->ws + WS_GLR);
;     float w2r[16];
; #pragma unroll
;     for (int j = 0; j < 16; ++j) w2r[j] = a->gate_w2[j * 512 + col];
;     const float bias = a->gate_b[col];
;     *(LAS f32x4*)(glrs + tid * 4) = *(const f32x4*)(glr + (size_t)t0 * 16 + tid * 4);
;     __syncthreads();
;     float run = 0.f;
; #pragma unroll
;     for (int r = 0; r < 32; ++r) { const LAS f32x4* gp = (const LAS f32x4*)(glrs + (seg * 32 + r) * 16);
;         float z = bias;
; #pragma unroll
;         for (int q = 0; q < 4; ++q) { const f32x4 g = gp[q]; z += g[0] * w2r[4 * q] + g[1] * w2r[4 * q + 1] + g[2] * w2r[4 * q + 2] + g[3] * w2r[4 * q + 3]; }
;         const float la = (fminf(z, 0.f) - __logf(1.0f + __expf(-fabsf(z)))) * (1.0f / 16.0f);
;         run += la; bc[r] = run; }
.LBB0_341:
	s_bfe_u32 s5, s10, 0x20005
	v_lshlrev_b32_e32 v2, 2, v8
	v_lshl_or_b32 v2, s5, 9, v2
	s_and_b32 s0, s2, 0xfffff000
	s_and_b32 s1, s3, 0xf80
	s_or_b32 s20, s0, s1
	s_nop 0
	s_nop 0
	s_ashr_i32 s21, s20, 31
	s_lshl_b64 s[0:1], s[20:21], 6
	s_nop 0
	v_lshl_add_u64 v[16:17], v[10:11], 0, s[0:1]
	s_barrier
	global_load_dwordx4 v[44:47], v[16:17], off
	s_mul_i32 s98, s5, 0x200
	v_and_b32_e32 v184, 31, v8
	v_and_b32_e32 v185, 64, v8
	v_or_b32_e32 v184, v184, v185
	v_bfe_u32 v185, v8, 5, 1
	v_lshlrev_b32_e32 v184, 2, v184
	v_lshl_add_u32 v184, v185, 11, v184
	v_add_u32_e32 v184, s98, v184
	global_load_dword v224, v184, s[12:13]
	global_load_dword v225, v184, s[12:13] offset:128
	v_add_u32_e32 v184, 0x1000, v184
	global_load_dword v226, v184, s[12:13]
	global_load_dword v227, v184, s[12:13] offset:128
	v_add_u32_e32 v184, 0x1000, v184
	global_load_dword v228, v184, s[12:13]
	global_load_dword v229, v184, s[12:13] offset:128
	v_add_u32_e32 v184, 0x1000, v184
	global_load_dword v230, v184, s[12:13]
	global_load_dword v231, v184, s[12:13] offset:128
	v_add_u32_e32 v184, 0x1000, v184
	global_load_dword v232, v184, s[12:13]
	global_load_dword v233, v184, s[12:13] offset:128
	v_add_u32_e32 v184, 0x1000, v184
	global_load_dword v234, v184, s[12:13]
	global_load_dword v235, v184, s[12:13] offset:128
	v_add_u32_e32 v184, 0x1000, v184
	global_load_dword v236, v184, s[12:13]
	global_load_dword v237, v184, s[12:13] offset:128
	v_add_u32_e32 v184, 0x1000, v184
	global_load_dword v238, v184, s[12:13]
	global_load_dword v239, v184, s[12:13] offset:128
	s_nop 0
	s_nop 0
	s_nop 0
	s_nop 0
	s_nop 0
	v_readfirstlane_b32 s1, v32
	s_nop 0
	s_nop 0
	s_nop 0
	s_nop 0
	s_nop 0
	global_load_dword v2, v2, s[14:15]
	s_ashr_i32 s0, s1, 7
	s_lshl_b32 s6, s0, 11
	s_add_i32 s6, s6, 0
	v_mov_b32_e32 v42, s6
	s_and_b32 s1, s1, 0x3fffff80
	s_cmp_gt_i32 s0, 0
	s_waitcnt vmcnt(17)
	ds_write_b128 v33, v[44:47] offset:34816
	s_waitcnt lgkmcnt(0)
	s_barrier
	v_and_b32_e32 v184, 63, v186
	v_and_b32_e32 v185, 31, v184
	v_lshrrev_b32_e32 v240, 5, v184
	v_lshlrev_b32_e32 v241, 6, v185
	v_lshl_add_u32 v241, v240, 2, v241
	v_add_u32_e32 v241, v42, v241
	ds_read_b32 v176, v241 offset:34816
	ds_read_b32 v177, v241 offset:34824
	ds_read_b32 v178, v241 offset:34832
	ds_read_b32 v179, v241 offset:34840
	ds_read_b32 v180, v241 offset:34848
	ds_read_b32 v181, v241 offset:34856
	ds_read_b32 v182, v241 offset:34864
	ds_read_b32 v183, v241 offset:34872
	s_waitcnt lgkmcnt(0)
	s_waitcnt vmcnt(16)
	v_mfma_f32_32x32x2_f32 v[144:159], v176, v224, 0
	s_waitcnt vmcnt(15)
	v_mfma_f32_32x32x2_f32 v[160:175], v176, v225, 0
	s_waitcnt vmcnt(14)
	v_mfma_f32_32x32x2_f32 v[144:159], v177, v226, v[144:159]
	s_waitcnt vmcnt(13)
	v_mfma_f32_32x32x2_f32 v[160:175], v177, v227, v[160:175]
	s_waitcnt vmcnt(12)
	v_mfma_f32_32x32x2_f32 v[144:159], v178, v228, v[144:159]
	s_waitcnt vmcnt(11)
	v_mfma_f32_32x32x2_f32 v[160:175], v178, v229, v[160:175]
	s_waitcnt vmcnt(10)
	v_mfma_f32_32x32x2_f32 v[144:159], v179, v230, v[144:159]
	s_waitcnt vmcnt(9)
	v_mfma_f32_32x32x2_f32 v[160:175], v179, v231, v[160:175]
	s_waitcnt vmcnt(8)
	v_mfma_f32_32x32x2_f32 v[144:159], v180, v232, v[144:159]
	s_waitcnt vmcnt(7)
	v_mfma_f32_32x32x2_f32 v[160:175], v180, v233, v[160:175]
	s_waitcnt vmcnt(6)
	v_mfma_f32_32x32x2_f32 v[144:159], v181, v234, v[144:159]
	s_waitcnt vmcnt(5)
	v_mfma_f32_32x32x2_f32 v[160:175], v181, v235, v[160:175]
	s_waitcnt vmcnt(4)
	v_mfma_f32_32x32x2_f32 v[144:159], v182, v236, v[144:159]
	s_waitcnt vmcnt(3)
	v_mfma_f32_32x32x2_f32 v[160:175], v182, v237, v[160:175]
	s_waitcnt vmcnt(2)
	v_mfma_f32_32x32x2_f32 v[144:159], v183, v238, v[144:159]
	s_waitcnt vmcnt(1)
	v_mfma_f32_32x32x2_f32 v[160:175], v183, v239, v[160:175]
	s_nop 15
	s_nop 3
	v_permlane32_swap_b32_e32 v144, v160
	v_permlane32_swap_b32_e32 v145, v161
	v_permlane32_swap_b32_e32 v146, v162
	v_permlane32_swap_b32_e32 v147, v163
	v_permlane32_swap_b32_e32 v148, v164
	v_permlane32_swap_b32_e32 v149, v165
	v_permlane32_swap_b32_e32 v150, v166
	v_permlane32_swap_b32_e32 v151, v167
	v_permlane32_swap_b32_e32 v152, v168
	v_permlane32_swap_b32_e32 v153, v169
	v_permlane32_swap_b32_e32 v154, v170
	v_permlane32_swap_b32_e32 v155, v171
	v_permlane32_swap_b32_e32 v156, v172
	v_permlane32_swap_b32_e32 v157, v173
	v_permlane32_swap_b32_e32 v158, v174
	v_permlane32_swap_b32_e32 v159, v175
	s_waitcnt vmcnt(0)
; #define LAS __attribute__((address_space(3)))
; __device__ __forceinline__ float bf2f(bf16_t v) { return __uint_as_float((unsigned)v << 16); }
; __device__ __forceinline__ void gla_bcum(KArgs a, int tid, int t0, int h, LAS float* segtot, LAS float* glrs, float (&bc)[32], float& tot) {
;     ...
;     for (int r = 0; r < 32; ++r) { const LAS f32x4* gp = (const LAS f32x4*)(glrs + (seg * 32 + r) * 16);
;         float z = bias;
; #pragma unroll
;         for (int q = 0; q < 4; ++q) { const f32x4 g = gp[q]; z += g[0] * w2r[4 * q] + g[1] * w2r[4 * q + 1] + g[2] * w2r[4 * q + 2] + g[3] * w2r[4 * q + 3]; }
;         const float la = (fminf(z, 0.f) - __logf(1.0f + __expf(-fabsf(z)))) * (1.0f / 16.0f);
;         run += la; bc[r] = run; }
; __device__ __forceinline__ void gla_a1(const Ctx& X, KArgs a, float* kvt, float* decb) {
;     ...
;               for (int e = 0; e < 8; ++e) { const int r = r8 * 8 + e; kd[e] = bf2f(proj[(size_t)(t0 + seg * 32 + r) * NMAIN + C_GK + h * 128 + d]) * __expf(tot - bc[r]); }
	v_add_f32_e32 v144, v2, v144
	v_add_f32_e32 v160, v2, v160
	v_add_f32_e32 v145, v2, v145
	v_add_f32_e32 v161, v2, v161
	v_add_f32_e32 v146, v2, v146
	v_add_f32_e32 v162, v2, v162
	v_add_f32_e32 v147, v2, v147
	v_add_f32_e32 v163, v2, v163
	v_add_f32_e32 v148, v2, v148
	v_add_f32_e32 v164, v2, v164
	v_add_f32_e32 v149, v2, v149
	v_add_f32_e32 v165, v2, v165
	v_add_f32_e32 v150, v2, v150
	v_add_f32_e32 v166, v2, v166
	v_add_f32_e32 v151, v2, v151
	v_add_f32_e32 v167, v2, v167
	v_add_f32_e32 v152, v2, v152
	v_add_f32_e32 v168, v2, v168
	v_add_f32_e32 v153, v2, v153
	v_add_f32_e32 v169, v2, v169
	v_add_f32_e32 v154, v2, v154
	v_add_f32_e32 v170, v2, v170
	v_add_f32_e32 v155, v2, v155
	v_add_f32_e32 v171, v2, v171
	v_add_f32_e32 v156, v2, v156
	v_add_f32_e32 v172, v2, v172
	v_add_f32_e32 v157, v2, v157
	v_add_f32_e32 v173, v2, v173
	v_add_f32_e32 v158, v2, v158
	v_add_f32_e32 v174, v2, v174
	v_add_f32_e32 v159, v2, v159
	v_add_f32_e32 v175, v2, v175
	v_add_u32_e32 v178, s20, v35
	v_mov_b64_e32 v[176:177], s[18:19]
	v_mad_i64_i32 v[176:177], s[100:101], v178, s35, v[176:177]
	s_mul_i32 s98, s5, 0x100
	s_mov_b32 s99, 0
	v_lshl_add_u64 v[176:177], v[176:177], 0, s[98:99]
	v_lshlrev_b32_e32 v178, 1, v8
	v_mov_b32_e32 v179, 0
	v_lshl_add_u64 v[176:177], v[176:177], 0, v[178:179]
	s_movk_i32 s98, 0x2a00
	global_load_ushort v192, v[176:177], off offset:1024
	v_lshl_add_u64 v[176:177], v[176:177], 0, s[98:99]
	global_load_ushort v193, v[176:177], off offset:1024
	v_lshl_add_u64 v[176:177], v[176:177], 0, s[98:99]
	global_load_ushort v194, v[176:177], off offset:1024
	v_lshl_add_u64 v[176:177], v[176:177], 0, s[98:99]
	global_load_ushort v195, v[176:177], off offset:1024
	v_lshl_add_u64 v[176:177], v[176:177], 0, s[98:99]
	global_load_ushort v196, v[176:177], off offset:1024
	v_lshl_add_u64 v[176:177], v[176:177], 0, s[98:99]
	global_load_ushort v197, v[176:177], off offset:1024
	v_lshl_add_u64 v[176:177], v[176:177], 0, s[98:99]
	global_load_ushort v198, v[176:177], off offset:1024
	v_lshl_add_u64 v[176:177], v[176:177], 0, s[98:99]
	global_load_ushort v199, v[176:177], off offset:1024
	v_lshl_add_u64 v[176:177], v[176:177], 0, s[98:99]
	global_load_ushort v200, v[176:177], off offset:1024
	v_lshl_add_u64 v[176:177], v[176:177], 0, s[98:99]
	global_load_ushort v201, v[176:177], off offset:1024
	v_lshl_add_u64 v[176:177], v[176:177], 0, s[98:99]
	global_load_ushort v202, v[176:177], off offset:1024
	v_lshl_add_u64 v[176:177], v[176:177], 0, s[98:99]
	global_load_ushort v203, v[176:177], off offset:1024
	v_lshl_add_u64 v[176:177], v[176:177], 0, s[98:99]
	global_load_ushort v204, v[176:177], off offset:1024
	v_lshl_add_u64 v[176:177], v[176:177], 0, s[98:99]
	global_load_ushort v205, v[176:177], off offset:1024
	v_lshl_add_u64 v[176:177], v[176:177], 0, s[98:99]
	global_load_ushort v206, v[176:177], off offset:1024
	v_lshl_add_u64 v[176:177], v[176:177], 0, s[98:99]
	global_load_ushort v207, v[176:177], off offset:1024
	v_lshl_add_u64 v[176:177], v[176:177], 0, s[98:99]
	global_load_ushort v208, v[176:177], off offset:1024
	v_lshl_add_u64 v[176:177], v[176:177], 0, s[98:99]
	global_load_ushort v209, v[176:177], off offset:1024
	v_lshl_add_u64 v[176:177], v[176:177], 0, s[98:99]
	global_load_ushort v210, v[176:177], off offset:1024
	v_lshl_add_u64 v[176:177], v[176:177], 0, s[98:99]
	global_load_ushort v211, v[176:177], off offset:1024
	v_lshl_add_u64 v[176:177], v[176:177], 0, s[98:99]
	global_load_ushort v212, v[176:177], off offset:1024
	v_lshl_add_u64 v[176:177], v[176:177], 0, s[98:99]
	global_load_ushort v213, v[176:177], off offset:1024
	v_lshl_add_u64 v[176:177], v[176:177], 0, s[98:99]
	global_load_ushort v214, v[176:177], off offset:1024
	v_lshl_add_u64 v[176:177], v[176:177], 0, s[98:99]
	global_load_ushort v215, v[176:177], off offset:1024
	v_lshl_add_u64 v[176:177], v[176:177], 0, s[98:99]
	global_load_ushort v216, v[176:177], off offset:1024
	v_lshl_add_u64 v[176:177], v[176:177], 0, s[98:99]
	global_load_ushort v217, v[176:177], off offset:1024
	v_lshl_add_u64 v[176:177], v[176:177], 0, s[98:99]
	global_load_ushort v218, v[176:177], off offset:1024
	v_lshl_add_u64 v[176:177], v[176:177], 0, s[98:99]
	global_load_ushort v219, v[176:177], off offset:1024
	v_lshl_add_u64 v[176:177], v[176:177], 0, s[98:99]
	global_load_ushort v220, v[176:177], off offset:1024
	v_lshl_add_u64 v[176:177], v[176:177], 0, s[98:99]
	global_load_ushort v221, v[176:177], off offset:1024
	v_lshl_add_u64 v[176:177], v[176:177], 0, s[98:99]
	global_load_ushort v222, v[176:177], off offset:1024
	v_lshl_add_u64 v[176:177], v[176:177], 0, s[98:99]
	global_load_ushort v223, v[176:177], off offset:1024
	v_mul_f32_e64 v43, |v144|, s4
	v_exp_f32_e32 v43, v43
	s_nop 0
	v_add_f32_e32 v43, 1.0, v43
	v_min_f32_e32 v13, 0, v144
	s_nop 0
	v_log_f32_e32 v43, v43
	s_nop 0
	v_mul_f32_e32 v46, 0x3f317217, v43
	v_fma_f32 v54, v43, s36, -v46
	v_fmac_f32_e32 v54, 0x3377d1cf, v43
	v_fmac_f32_e32 v54, 0x3f317217, v43
	v_mul_f32_e64 v44, |v145|, s4
	v_exp_f32_e32 v44, v44
	v_mov_b32_e32 v43, v54
	v_add_f32_e32 v44, 1.0, v44
	v_sub_f32_e32 v13, v13, v43
	s_mov_b32 s8, 0x3d800000
	v_log_f32_e32 v58, v44
	v_fma_f32 v44, v13, s8, 0
	v_min_f32_e32 v13, 0, v145
	v_mul_f32_e32 v43, 0x3f317217, v58
	v_fma_f32 v43, v58, s36, -v43
	v_mul_f32_e64 v46, |v146|, s4
	v_exp_f32_e32 v46, v46
	v_fmac_f32_e32 v43, 0x3377d1cf, v58
	v_fmac_f32_e32 v43, 0x3f317217, v58
	v_mov_b32_e32 v43, v43
	v_add_f32_e32 v46, 1.0, v46
	v_sub_f32_e32 v13, v13, v43
	v_log_f32_e32 v47, v46
	v_fmamk_f32 v46, v13, 0x3d800000, v44
	v_min_f32_e32 v13, 0, v146
	v_mul_f32_e32 v43, 0x3f317217, v47
	v_fma_f32 v43, v47, s36, -v43
; #define LAS __attribute__((address_space(3)))
; __device__ __forceinline__ void gla_bcum(KArgs a, int tid, int t0, int h, LAS float* segtot, LAS float* glrs, float (&bc)[32], float& tot) {
;     ...
;     for (int r = 0; r < 32; ++r) { const LAS f32x4* gp = (const LAS f32x4*)(glrs + (seg * 32 + r) * 16);
;         float z = bias;
; #pragma unroll
;         for (int q = 0; q < 4; ++q) { const f32x4 g = gp[q]; z += g[0] * w2r[4 * q] + g[1] * w2r[4 * q + 1] + g[2] * w2r[4 * q + 2] + g[3] * w2r[4 * q + 3]; }
;         const float la = (fminf(z, 0.f) - __logf(1.0f + __expf(-fabsf(z)))) * (1.0f / 16.0f);
;         run += la; bc[r] = run; }
	v_mul_f32_e64 v48, |v147|, s4
	v_exp_f32_e32 v48, v48
	v_fmac_f32_e32 v43, 0x3377d1cf, v47
	v_fmac_f32_e32 v43, 0x3f317217, v47
	s_nop 1
	v_mov_b32_e32 v43, v43
	v_add_f32_e32 v47, 1.0, v48
	v_sub_f32_e32 v13, v13, v43
	v_min_f32_e32 v43, 0, v147
	v_log_f32_e32 v47, v47
	v_fmamk_f32 v13, v13, 0x3d800000, v46
	v_mul_f32_e32 v45, 0x3f317217, v47
	v_fma_f32 v45, v47, s36, -v45
	v_fmac_f32_e32 v45, 0x3377d1cf, v47
	v_mul_f32_e64 v49, |v160|, s4
	v_exp_f32_e32 v49, v49
	v_fmac_f32_e32 v45, 0x3f317217, v47
	s_nop 1
	v_mov_b32_e32 v45, v45
	v_add_f32_e32 v47, 1.0, v49
	v_sub_f32_e32 v43, v43, v45
	v_min_f32_e32 v45, 0, v160
	v_log_f32_e32 v47, v47
	v_fmamk_f32 v43, v43, 0x3d800000, v13
	v_mul_f32_e32 v56, 0x3f317217, v47
	v_fma_f32 v60, v47, s36, -v56
	v_fmac_f32_e32 v60, 0x3377d1cf, v47
	v_fmac_f32_e32 v60, 0x3f317217, v47
	v_mul_f32_e64 v49, |v161|, s4
	v_exp_f32_e32 v49, v49
	v_mov_b32_e32 v47, v60
	v_add_f32_e32 v49, 1.0, v49
	v_sub_f32_e32 v45, v45, v47
	v_min_f32_e32 v47, 0, v161
	v_log_f32_e32 v60, v49
	v_fmamk_f32 v45, v45, 0x3d800000, v43
	v_mul_f32_e32 v56, 0x3f317217, v60
	v_fma_f32 v61, v60, s36, -v56
	v_fmac_f32_e32 v61, 0x3377d1cf, v60
	v_fmac_f32_e32 v61, 0x3f317217, v60
	v_mul_f32_e64 v49, |v162|, s4
	v_exp_f32_e32 v49, v49
	v_mov_b32_e32 v50, v61
	v_add_f32_e32 v49, 1.0, v49
	v_sub_f32_e32 v47, v47, v50
	v_min_f32_e32 v61, 0, v162
	v_log_f32_e32 v60, v49
	v_fmamk_f32 v47, v47, 0x3d800000, v45
	v_mul_f32_e32 v56, 0x3f317217, v60
	v_fma_f32 v62, v60, s36, -v56
	v_fmac_f32_e32 v62, 0x3377d1cf, v60
	v_fmac_f32_e32 v62, 0x3f317217, v60
	v_mul_f32_e64 v48, |v163|, s4
	v_exp_f32_e32 v48, v48
	v_mov_b32_e32 v50, v62
	v_add_f32_e32 v48, 1.0, v48
	v_min_f32_e32 v49, 0, v163
	s_nop 0
	v_log_f32_e32 v62, v48
	v_sub_f32_e32 v48, v61, v50
	v_fmamk_f32 v48, v48, 0x3d800000, v47
	v_mul_f32_e32 v58, 0x3f317217, v62
	v_fma_f32 v63, v62, s36, -v58
	v_fmac_f32_e32 v63, 0x3377d1cf, v62
	v_fmac_f32_e32 v63, 0x3f317217, v62
	v_mul_f32_e64 v51, |v148|, s4
	v_exp_f32_e32 v51, v51
	s_nop 0
	v_add_f32_e32 v51, 1.0, v51
	v_mov_b32_e32 v52, v63
	v_min_f32_e32 v63, 0, v148
	v_log_f32_e32 v62, v51
	v_mov_b32_e32 v51, v52
	v_sub_f32_e32 v49, v49, v51
	v_mul_f32_e32 v58, 0x3f317217, v62
	v_fma_f32 v64, v62, s36, -v58
	v_fmac_f32_e32 v64, 0x3377d1cf, v62
	v_fmac_f32_e32 v64, 0x3f317217, v62
	v_mul_f32_e64 v50, |v149|, s4
	v_exp_f32_e32 v50, v50
	v_mov_b32_e32 v52, v64
	v_min_f32_e32 v51, 0, v149
	v_add_f32_e32 v50, 1.0, v50
	s_nop 1
	v_log_f32_e32 v64, v50
	v_mov_b32_e32 v50, v52
	v_sub_f32_e32 v50, v63, v50
	v_mul_f32_e32 v60, 0x3f317217, v64
	v_fma_f32 v65, v64, s36, -v60
	v_fmac_f32_e32 v65, 0x3377d1cf, v64
	v_fmac_f32_e32 v65, 0x3f317217, v64
	v_mul_f32_e64 v53, |v150|, s4
	v_exp_f32_e32 v53, v53
	s_nop 0
	v_add_f32_e32 v53, 1.0, v53
	v_mov_b32_e32 v54, v65
	v_min_f32_e32 v65, 0, v150
	v_log_f32_e32 v64, v53
	v_mov_b32_e32 v53, v54
	v_sub_f32_e32 v51, v51, v53
	v_mul_f32_e32 v60, 0x3f317217, v64
	v_fma_f32 v66, v64, s36, -v60
	v_fmac_f32_e32 v66, 0x3377d1cf, v64
	v_fmac_f32_e32 v66, 0x3f317217, v64
	v_mul_f32_e64 v52, |v151|, s4
	v_exp_f32_e32 v52, v52
	v_mov_b32_e32 v54, v66
	v_min_f32_e32 v53, 0, v151
	v_add_f32_e32 v52, 1.0, v52
	s_nop 1
	v_log_f32_e32 v66, v52
	v_mov_b32_e32 v52, v54
	v_sub_f32_e32 v52, v65, v52
	v_mul_f32_e32 v62, 0x3f317217, v66
	v_fma_f32 v67, v66, s36, -v62
	v_fmac_f32_e32 v67, 0x3377d1cf, v66
	v_fmac_f32_e32 v67, 0x3f317217, v66
	v_mul_f32_e64 v55, |v164|, s4
	v_exp_f32_e32 v55, v55
	s_nop 0
	v_add_f32_e32 v55, 1.0, v55
	v_mov_b32_e32 v56, v67
	v_min_f32_e32 v67, 0, v164
	v_log_f32_e32 v66, v55
	v_mov_b32_e32 v55, v56
	v_sub_f32_e32 v53, v53, v55
	v_mul_f32_e32 v62, 0x3f317217, v66
	v_fma_f32 v68, v66, s36, -v62
	v_fmac_f32_e32 v68, 0x3377d1cf, v66
	v_fmac_f32_e32 v68, 0x3f317217, v66
	v_mul_f32_e64 v54, |v165|, s4
	v_exp_f32_e32 v54, v54
	v_mov_b32_e32 v56, v68
	v_min_f32_e32 v55, 0, v165
	v_add_f32_e32 v54, 1.0, v54
	s_nop 1
	v_log_f32_e32 v68, v54
	v_mov_b32_e32 v54, v56
	v_sub_f32_e32 v54, v67, v54
	v_mul_f32_e32 v64, 0x3f317217, v68
	v_fma_f32 v69, v68, s36, -v64
	v_fmac_f32_e32 v69, 0x3377d1cf, v68
	v_fmac_f32_e32 v69, 0x3f317217, v68
	v_mul_f32_e64 v57, |v166|, s4
	v_exp_f32_e32 v57, v57
	s_nop 0
	v_add_f32_e32 v57, 1.0, v57
	v_mov_b32_e32 v58, v69
	v_min_f32_e32 v69, 0, v166
	v_log_f32_e32 v68, v57
	v_mov_b32_e32 v57, v58
	v_sub_f32_e32 v55, v55, v57
	v_mul_f32_e32 v64, 0x3f317217, v68
	v_fma_f32 v70, v68, s36, -v64
	v_fmac_f32_e32 v70, 0x3377d1cf, v68
	v_fmac_f32_e32 v70, 0x3f317217, v68
	v_mul_f32_e64 v56, |v167|, s4
	v_exp_f32_e32 v56, v56
	v_mov_b32_e32 v58, v70
	v_min_f32_e32 v57, 0, v167
	v_add_f32_e32 v56, 1.0, v56
	s_nop 1
	v_log_f32_e32 v70, v56
	v_mov_b32_e32 v56, v58
	v_sub_f32_e32 v56, v69, v56
	v_mul_f32_e32 v66, 0x3f317217, v70
	v_fma_f32 v71, v70, s36, -v66
	v_fmac_f32_e32 v71, 0x3377d1cf, v70
	v_fmac_f32_e32 v71, 0x3f317217, v70
	v_mul_f32_e64 v59, |v152|, s4
	v_exp_f32_e32 v59, v59
	s_nop 0
	v_add_f32_e32 v59, 1.0, v59
	v_mov_b32_e32 v60, v71
	v_min_f32_e32 v71, 0, v152
	v_log_f32_e32 v70, v59
	v_mov_b32_e32 v59, v60
	v_sub_f32_e32 v57, v57, v59
	v_mul_f32_e32 v66, 0x3f317217, v70
	v_fma_f32 v72, v70, s36, -v66
	v_fmac_f32_e32 v72, 0x3377d1cf, v70
	v_fmac_f32_e32 v72, 0x3f317217, v70
	v_mul_f32_e64 v58, |v153|, s4
	v_exp_f32_e32 v58, v58
	v_mov_b32_e32 v60, v72
	v_min_f32_e32 v59, 0, v153
	v_add_f32_e32 v58, 1.0, v58
	s_nop 1
	v_log_f32_e32 v72, v58
	v_mov_b32_e32 v58, v60
	v_sub_f32_e32 v58, v71, v58
	v_mul_f32_e32 v68, 0x3f317217, v72
	v_fma_f32 v73, v72, s36, -v68
	v_fmac_f32_e32 v73, 0x3377d1cf, v72
	v_fmac_f32_e32 v73, 0x3f317217, v72
	v_mul_f32_e64 v61, |v154|, s4
	v_exp_f32_e32 v61, v61
	s_nop 0
; #define LAS __attribute__((address_space(3)))
; __device__ __forceinline__ void gla_bcum(KArgs a, int tid, int t0, int h, LAS float* segtot, LAS float* glrs, float (&bc)[32], float& tot) {
;     ...
;     for (int r = 0; r < 32; ++r) { const LAS f32x4* gp = (const LAS f32x4*)(glrs + (seg * 32 + r) * 16);
;         float z = bias;
; #pragma unroll
;         for (int q = 0; q < 4; ++q) { const f32x4 g = gp[q]; z += g[0] * w2r[4 * q] + g[1] * w2r[4 * q + 1] + g[2] * w2r[4 * q + 2] + g[3] * w2r[4 * q + 3]; }
;         const float la = (fminf(z, 0.f) - __logf(1.0f + __expf(-fabsf(z)))) * (1.0f / 16.0f);
;         run += la; bc[r] = run; }
;     segtot[seg * 128 + d] = run;
;     __syncthreads();
	v_add_f32_e32 v61, 1.0, v61
	v_mov_b32_e32 v62, v73
	v_min_f32_e32 v73, 0, v154
	v_log_f32_e32 v72, v61
	v_mov_b32_e32 v61, v62
	v_sub_f32_e32 v59, v59, v61
	v_mul_f32_e32 v68, 0x3f317217, v72
	v_fma_f32 v74, v72, s36, -v68
	v_fmac_f32_e32 v74, 0x3377d1cf, v72
	v_fmac_f32_e32 v74, 0x3f317217, v72
	v_mul_f32_e64 v60, |v155|, s4
	v_exp_f32_e32 v60, v60
	v_mov_b32_e32 v62, v74
	v_min_f32_e32 v61, 0, v155
	v_add_f32_e32 v60, 1.0, v60
	s_nop 1
	v_log_f32_e32 v74, v60
	v_mov_b32_e32 v60, v62
	v_sub_f32_e32 v60, v73, v60
	v_mul_f32_e32 v70, 0x3f317217, v74
	v_fma_f32 v75, v74, s36, -v70
	v_fmac_f32_e32 v75, 0x3377d1cf, v74
	v_fmac_f32_e32 v75, 0x3f317217, v74
	v_mul_f32_e64 v63, |v168|, s4
	v_exp_f32_e32 v63, v63
	s_nop 0
	v_add_f32_e32 v63, 1.0, v63
	v_mov_b32_e32 v64, v75
	v_min_f32_e32 v75, 0, v168
	v_log_f32_e32 v74, v63
	v_mov_b32_e32 v63, v64
	v_sub_f32_e32 v61, v61, v63
	v_mul_f32_e32 v70, 0x3f317217, v74
	v_fma_f32 v76, v74, s36, -v70
	v_fmac_f32_e32 v76, 0x3377d1cf, v74
	v_fmac_f32_e32 v76, 0x3f317217, v74
	v_mul_f32_e64 v62, |v169|, s4
	v_exp_f32_e32 v62, v62
	v_mov_b32_e32 v64, v76
	v_min_f32_e32 v63, 0, v169
	v_add_f32_e32 v62, 1.0, v62
	s_nop 1
	v_log_f32_e32 v76, v62
	v_mov_b32_e32 v62, v64
	v_sub_f32_e32 v62, v75, v62
	v_mul_f32_e32 v72, 0x3f317217, v76
	v_fma_f32 v77, v76, s36, -v72
	v_fmac_f32_e32 v77, 0x3377d1cf, v76
	v_fmac_f32_e32 v77, 0x3f317217, v76
	v_mul_f32_e64 v65, |v170|, s4
	v_exp_f32_e32 v65, v65
	s_nop 0
	v_add_f32_e32 v65, 1.0, v65
	v_mov_b32_e32 v66, v77
	v_min_f32_e32 v77, 0, v170
	v_log_f32_e32 v76, v65
	v_mov_b32_e32 v65, v66
	v_sub_f32_e32 v63, v63, v65
	v_mul_f32_e32 v72, 0x3f317217, v76
	v_fma_f32 v78, v76, s36, -v72
	v_fmac_f32_e32 v78, 0x3377d1cf, v76
	v_fmac_f32_e32 v78, 0x3f317217, v76
	v_mul_f32_e64 v64, |v171|, s4
	v_exp_f32_e32 v64, v64
	v_mov_b32_e32 v66, v78
	v_min_f32_e32 v65, 0, v171
	v_add_f32_e32 v64, 1.0, v64
	s_nop 1
	v_log_f32_e32 v78, v64
	v_mov_b32_e32 v64, v66
	v_sub_f32_e32 v64, v77, v64
	v_mul_f32_e32 v74, 0x3f317217, v78
	v_fma_f32 v79, v78, s36, -v74
	v_fmac_f32_e32 v79, 0x3377d1cf, v78
	v_fmac_f32_e32 v79, 0x3f317217, v78
	v_mul_f32_e64 v67, |v156|, s4
	v_exp_f32_e32 v67, v67
	s_nop 0
	v_add_f32_e32 v67, 1.0, v67
	v_mov_b32_e32 v68, v79
	v_min_f32_e32 v79, 0, v156
	v_log_f32_e32 v78, v67
	v_mov_b32_e32 v67, v68
	v_sub_f32_e32 v65, v65, v67
	v_mul_f32_e32 v74, 0x3f317217, v78
	v_fma_f32 v80, v78, s36, -v74
	v_fmac_f32_e32 v80, 0x3377d1cf, v78
	v_fmac_f32_e32 v80, 0x3f317217, v78
	v_mul_f32_e64 v67, |v157|, s4
	v_exp_f32_e32 v67, v67
	v_mov_b32_e32 v68, v80
	v_min_f32_e32 v80, 0, v157
	v_add_f32_e32 v67, 1.0, v67
	s_nop 1
	v_log_f32_e32 v78, v67
	v_mov_b32_e32 v67, v68
	v_sub_f32_e32 v79, v79, v67
	v_mul_f32_e32 v74, 0x3f317217, v78
	v_fma_f32 v81, v78, s36, -v74
	v_fmac_f32_e32 v81, 0x3377d1cf, v78
	v_fmac_f32_e32 v81, 0x3f317217, v78
	v_mul_f32_e64 v67, |v158|, s4
	v_exp_f32_e32 v67, v67
	v_mov_b32_e32 v68, v81
	v_min_f32_e32 v81, 0, v158
	v_add_f32_e32 v67, 1.0, v67
	s_nop 1
	v_log_f32_e32 v78, v67
	v_mov_b32_e32 v67, v68
	v_sub_f32_e32 v80, v80, v67
	v_mul_f32_e32 v74, 0x3f317217, v78
	v_fma_f32 v82, v78, s36, -v74
	v_fmac_f32_e32 v82, 0x3377d1cf, v78
	v_fmac_f32_e32 v82, 0x3f317217, v78
	v_mul_f32_e64 v67, |v159|, s4
	v_exp_f32_e32 v67, v67
	v_mov_b32_e32 v68, v82
	v_min_f32_e32 v82, 0, v159
	v_add_f32_e32 v67, 1.0, v67
	s_nop 1
	v_log_f32_e32 v78, v67
	v_mov_b32_e32 v67, v68
	v_sub_f32_e32 v81, v81, v67
	v_mul_f32_e32 v74, 0x3f317217, v78
	v_fma_f32 v83, v78, s36, -v74
	v_fmac_f32_e32 v83, 0x3377d1cf, v78
	v_fmac_f32_e32 v83, 0x3f317217, v78
	v_mul_f32_e64 v67, |v172|, s4
	v_exp_f32_e32 v67, v67
	v_mov_b32_e32 v68, v83
	v_min_f32_e32 v83, 0, v172
	v_add_f32_e32 v67, 1.0, v67
	s_nop 1
	v_log_f32_e32 v78, v67
	v_mov_b32_e32 v67, v68
	v_sub_f32_e32 v82, v82, v67
	v_mul_f32_e32 v74, 0x3f317217, v78
	v_fma_f32 v84, v78, s36, -v74
	v_fmac_f32_e32 v84, 0x3377d1cf, v78
	v_fmac_f32_e32 v84, 0x3f317217, v78
	v_mul_f32_e64 v67, |v173|, s4
	v_exp_f32_e32 v67, v67
	v_mov_b32_e32 v68, v84
	v_min_f32_e32 v84, 0, v173
	v_add_f32_e32 v67, 1.0, v67
	s_nop 1
	v_log_f32_e32 v78, v67
	v_mov_b32_e32 v67, v68
	v_sub_f32_e32 v83, v83, v67
	v_mul_f32_e32 v74, 0x3f317217, v78
	v_fma_f32 v85, v78, s36, -v74
	v_fmac_f32_e32 v85, 0x3377d1cf, v78
	v_fmac_f32_e32 v85, 0x3f317217, v78
	v_mul_f32_e64 v67, |v174|, s4
	v_exp_f32_e32 v67, v67
	v_mov_b32_e32 v68, v85
	v_min_f32_e32 v78, 0, v174
	v_add_f32_e32 v67, 1.0, v67
	s_nop 1
	v_log_f32_e32 v76, v67
	v_mov_b32_e32 v67, v68
	v_sub_f32_e32 v77, v84, v67
	v_mul_f32_e32 v74, 0x3f317217, v76
	v_fma_f32 v84, v76, s36, -v74
	v_fmac_f32_e32 v84, 0x3377d1cf, v76
	v_fmac_f32_e32 v84, 0x3f317217, v76
	s_nop 0
	v_mul_f32_e64 v14, |v175|, s4
	v_exp_f32_e32 v14, v14
	v_mov_b32_e32 v15, v84
	v_sub_f32_e32 v15, v78, v15
	v_add_f32_e32 v14, 1.0, v14
	v_min_f32_e32 v2, 0, v175
	s_nop 0
	v_fmamk_f32 v17, v49, 0x3d800000, v48
	v_fmamk_f32 v42, v50, 0x3d800000, v17
	v_fmamk_f32 v49, v51, 0x3d800000, v42
	v_fmamk_f32 v66, v52, 0x3d800000, v49
	v_fmamk_f32 v67, v53, 0x3d800000, v66
	v_fmamk_f32 v68, v54, 0x3d800000, v67
	v_fmamk_f32 v69, v55, 0x3d800000, v68
	v_fmamk_f32 v70, v56, 0x3d800000, v69
	v_fmamk_f32 v71, v57, 0x3d800000, v70
	v_fmamk_f32 v58, v58, 0x3d800000, v71
	v_fmamk_f32 v59, v59, 0x3d800000, v58
	v_fmamk_f32 v60, v60, 0x3d800000, v59
	v_fmamk_f32 v61, v61, 0x3d800000, v60
	v_log_f32_e32 v14, v14
	v_fmamk_f32 v62, v62, 0x3d800000, v61
	v_fmamk_f32 v63, v63, 0x3d800000, v62
	v_fmamk_f32 v64, v64, 0x3d800000, v63
	v_fmamk_f32 v65, v65, 0x3d800000, v64
	v_mul_f32_e32 v16, 0x3f317217, v14
	v_fmamk_f32 v72, v79, 0x3d800000, v65
	v_fma_f32 v16, v14, s36, -v16
	v_fmamk_f32 v73, v80, 0x3d800000, v72
	v_fmac_f32_e32 v16, 0x3377d1cf, v14
	v_fmamk_f32 v74, v81, 0x3d800000, v73
	v_fmac_f32_e32 v16, 0x3f317217, v14
	v_fmamk_f32 v75, v82, 0x3d800000, v74
	v_fmamk_f32 v76, v83, 0x3d800000, v75
	v_mov_b32_e32 v14, v16
	v_fmamk_f32 v77, v77, 0x3d800000, v76
	v_sub_f32_e32 v2, v2, v14
	v_fmamk_f32 v78, v15, 0x3d800000, v77
	v_lshl_add_u32 v14, s1, 2, v34
	v_fmamk_f32 v79, v2, 0x3d800000, v78
	ds_write_b32 v14, v79
	s_waitcnt lgkmcnt(0)
	s_barrier
; #define LAS __attribute__((address_space(3)))
; __device__ __forceinline__ float bf2f(bf16_t v) { return __uint_as_float((unsigned)v << 16); }
; __device__ __forceinline__ u32x4 pack8(const float* f) { u32x4 w; w.x = pk2(f[0], f[1]); w.y = pk2(f[2], f[3]); w.z = pk2(f[4], f[5]); w.w = pk2(f[6], f[7]); return w; }
; #define X make_ctx(lds_raw)
; __device__ __forceinline__ void gla_bcum(KArgs a, int tid, int t0, int h, LAS float* segtot, LAS float* glrs, float (&bc)[32], float& tot) {
;     ...
;     float off = 0.f; tot = 0.f;
; #pragma unroll
;     for (int s2 = 0; s2 < 4; ++s2) { const float v = segtot[s2 * 128 + d]; tot += v; if (s2 < seg) off += v; }
; #pragma unroll
;     for (int r = 0; r < 32; ++r) bc[r] += off;
; __device__ __forceinline__ void gla_a1(const Ctx& X, KArgs a, float* kvt, float* decb) {
;     ...
;         { const int d = X.tid & 127, seg = X.tid >> 7;
; #pragma unroll
;           for (int r8 = 0; r8 < 4; ++r8) { float kd[8];
; #pragma unroll
;               for (int e = 0; e < 8; ++e) { const int r = r8 * 8 + e; kd[e] = bf2f(proj[(size_t)(t0 + seg * 32 + r) * NMAIN + C_GK + h * 128 + d]) * __expf(tot - bc[r]); }
;               *(LAS u32x4*)(kdT + d * GP + seg * 32 + r8 * 8) = pack8(kd); }
	ds_read2st64_b32 v[14:15], v34 offset1:2
	ds_read2st64_b32 v[20:21], v34 offset0:4 offset1:6
	s_cselect_b64 s[6:7], -1, 0
	s_cmp_gt_i32 s0, 1
	s_waitcnt lgkmcnt(1)
	v_add_f32_e32 v2, 0, v14
	v_cndmask_b32_e64 v14, 0, v2, s[6:7]
	v_add_f32_e32 v16, v15, v14
	s_cselect_b64 s[6:7], -1, 0
	s_cmp_gt_i32 s0, 2
	v_cndmask_b32_e64 v14, v14, v16, s[6:7]
	s_waitcnt lgkmcnt(0)
	v_add_f32_e32 v18, v20, v14
	s_cselect_b64 s[6:7], -1, 0
	v_add_f32_e32 v2, v15, v2
	s_cmp_gt_i32 s0, 3
	v_add_f32_e32 v16, v20, v2
	v_cndmask_b32_e64 v2, v14, v18, s[6:7]
	v_add_f32_e32 v14, v21, v2
	s_cselect_b64 s[6:7], -1, 0
	v_cndmask_b32_e64 v19, v2, v14, s[6:7]
	s_nop 0
	s_nop 0
	s_nop 0
	v_mov_b32_e32 v18, v21
	v_add_f32_e32 v13, v13, v19
	v_pk_add_f32 v[16:17], v[18:19], v[16:17]
	v_add_f32_e32 v44, v44, v19
	v_add_f32_e32 v46, v46, v19
	v_sub_f32_e32 v13, v16, v13
	v_add_f32_e32 v25, v43, v19
	v_add_f32_e32 v26, v45, v19
	v_add_f32_e32 v27, v47, v19
	v_add_f32_e32 v28, v48, v19
	v_add_f32_e32 v21, v42, v19
	v_add_f32_e32 v42, v49, v19
	v_add_f32_e32 v43, v66, v19
	v_add_f32_e32 v55, v67, v19
	v_add_f32_e32 v56, v68, v19
	v_add_f32_e32 v57, v69, v19
	v_add_f32_e32 v66, v70, v19
	v_add_f32_e32 v67, v71, v19
	v_add_f32_e32 v58, v58, v19
	v_add_f32_e32 v59, v59, v19
	v_add_f32_e32 v60, v60, v19
	v_add_f32_e32 v61, v61, v19
	v_add_f32_e32 v62, v62, v19
	v_add_f32_e32 v63, v63, v19
	v_add_f32_e32 v64, v64, v19
	v_add_f32_e32 v65, v65, v19
	v_add_f32_e32 v68, v72, v19
	v_add_f32_e32 v69, v73, v19
	v_add_f32_e32 v70, v74, v19
	v_add_f32_e32 v71, v75, v19
	v_add_f32_e32 v72, v76, v19
	v_add_f32_e32 v73, v77, v19
	v_add_f32_e32 v74, v78, v19
	v_add_f32_e32 v75, v19, v79
	v_sub_f32_e32 v18, v16, v44
	v_sub_f32_e32 v19, v16, v46
	v_mul_f32_e32 v13, 0x3fb8aa3b, v13
	v_mul_f32_e32 v18, 0x3fb8aa3b, v18
	v_mul_f32_e32 v19, 0x3fb8aa3b, v19
	v_exp_f32_e32 v24, v13
	v_sub_f32_e32 v13, v16, v25
	v_exp_f32_e32 v18, v18
	v_exp_f32_e32 v19, v19
	v_mul_f32_e32 v13, 0x3fb8aa3b, v13
	v_exp_f32_e32 v25, v13
	s_waitcnt vmcnt(30)
	v_lshlrev_b32_e32 v23, 16, v193
	v_lshlrev_b32_e32 v22, 16, v192
	v_sub_f32_e32 v13, v16, v26
	v_pk_mul_f32 v[18:19], v[18:19], v[22:23]
	s_waitcnt vmcnt(28)
	v_lshlrev_b32_e32 v23, 16, v195
	v_lshlrev_b32_e32 v22, 16, v194
	v_mul_f32_e32 v13, 0x3fb8aa3b, v13
	v_pk_mul_f32 v[24:25], v[24:25], v[22:23]
	v_exp_f32_e32 v22, v13
	v_sub_f32_e32 v13, v16, v27
	v_mul_f32_e32 v13, 0x3fb8aa3b, v13
	v_exp_f32_e32 v23, v13
	v_sub_f32_e32 v13, v16, v28
	v_mul_f32_e32 v13, 0x3fb8aa3b, v13
	v_exp_f32_e32 v28, v13
	v_sub_f32_e32 v13, v16, v17
	v_mul_f32_e32 v13, 0x3fb8aa3b, v13
	v_exp_f32_e32 v29, v13
	s_waitcnt vmcnt(26)
	v_lshlrev_b32_e32 v27, 16, v197
	v_lshlrev_b32_e32 v26, 16, v196
	v_pk_mul_f32 v[26:27], v[22:23], v[26:27]
	s_waitcnt vmcnt(24)
	v_lshlrev_b32_e32 v23, 16, v199
	v_lshlrev_b32_e32 v22, 16, v198
	v_pk_mul_f32 v[28:29], v[28:29], v[22:23]
	v_cvt_pk_bf16_f32 v22, v18, v19
	v_cvt_pk_bf16_f32 v23, v24, v25
	v_cvt_pk_bf16_f32 v24, v26, v27
	v_cvt_pk_bf16_f32 v25, v28, v29
	v_sub_f32_e32 v13, v16, v21
	ds_write_b128 v37, v[22:25]
	v_mul_f32_e32 v13, 0x3fb8aa3b, v13
	v_exp_f32_e32 v18, v13
	v_sub_f32_e32 v13, v16, v42
	v_mul_f32_e32 v13, 0x3fb8aa3b, v13
	v_exp_f32_e32 v19, v13
	v_sub_f32_e32 v13, v16, v43
	s_waitcnt vmcnt(23)
	v_lshlrev_b32_e32 v22, 16, v200
	s_nop 0
	s_nop 0
	s_nop 0
	s_nop 0
	v_mul_f32_e32 v13, 0x3fb8aa3b, v13
	v_exp_f32_e32 v14, v13
	v_sub_f32_e32 v13, v16, v55
	v_mul_f32_e32 v13, 0x3fb8aa3b, v13
	v_exp_f32_e32 v15, v13
	v_sub_f32_e32 v13, v16, v56
	s_waitcnt vmcnt(20)
; #define LAS __attribute__((address_space(3)))
; __device__ __forceinline__ float bf2f(bf16_t v) { return __uint_as_float((unsigned)v << 16); }
; __device__ __forceinline__ u32x4 pack8(const float* f) { u32x4 w; w.x = pk2(f[0], f[1]); w.y = pk2(f[2], f[3]); w.z = pk2(f[4], f[5]); w.w = pk2(f[6], f[7]); return w; }
; __device__ __forceinline__ void gla_a1(const Ctx& X, KArgs a, float* kvt, float* decb) {
;     ...
;           for (int r8 = 0; r8 < 4; ++r8) { float kd[8];
; #pragma unroll
;               for (int e = 0; e < 8; ++e) { const int r = r8 * 8 + e; kd[e] = bf2f(proj[(size_t)(t0 + seg * 32 + r) * NMAIN + C_GK + h * 128 + d]) * __expf(tot - bc[r]); }
;               *(LAS u32x4*)(kdT + d * GP + seg * 32 + r8 * 8) = pack8(kd); }
;           if (seg == 0) decb[unit * 128 + d] = __expf(tot); }
	v_lshlrev_b32_e32 v21, 16, v203
	v_lshlrev_b32_e32 v20, 16, v202
	v_mul_f32_e32 v13, 0x3fb8aa3b, v13
	v_pk_mul_f32 v[14:15], v[14:15], v[20:21]
	v_exp_f32_e32 v20, v13
	v_sub_f32_e32 v13, v16, v57
	v_mul_f32_e32 v13, 0x3fb8aa3b, v13
	v_exp_f32_e32 v21, v13
	v_sub_f32_e32 v13, v16, v66
	v_mul_f32_e32 v13, 0x3fb8aa3b, v13
	v_exp_f32_e32 v24, v13
	v_sub_f32_e32 v13, v16, v67
	v_mul_f32_e32 v13, 0x3fb8aa3b, v13
	v_lshlrev_b32_e32 v23, 16, v201
	v_exp_f32_e32 v25, v13
	v_sub_f32_e32 v13, v16, v58
	v_pk_mul_f32 v[18:19], v[18:19], v[22:23]
	v_mul_f32_e32 v13, 0x3fb8aa3b, v13
	s_waitcnt vmcnt(18)
	v_lshlrev_b32_e32 v23, 16, v205
	v_lshlrev_b32_e32 v22, 16, v204
	v_cvt_pk_bf16_f32 v18, v18, v19
	v_cvt_pk_bf16_f32 v19, v14, v15
	v_exp_f32_e32 v14, v13
	v_sub_f32_e32 v13, v16, v59
	v_pk_mul_f32 v[20:21], v[20:21], v[22:23]
	s_waitcnt vmcnt(16)
	v_lshlrev_b32_e32 v23, 16, v207
	v_lshlrev_b32_e32 v22, 16, v206
	v_mul_f32_e32 v13, 0x3fb8aa3b, v13
	v_pk_mul_f32 v[22:23], v[24:25], v[22:23]
	v_exp_f32_e32 v15, v13
	v_sub_f32_e32 v13, v16, v60
	v_cvt_pk_bf16_f32 v20, v20, v21
	v_cvt_pk_bf16_f32 v21, v22, v23
	v_mul_f32_e32 v13, 0x3fb8aa3b, v13
	ds_write_b128 v37, v[18:21] offset:16
	v_exp_f32_e32 v20, v13
	v_sub_f32_e32 v13, v16, v61
	v_mul_f32_e32 v13, 0x3fb8aa3b, v13
	v_exp_f32_e32 v21, v13
	s_waitcnt vmcnt(14)
	v_lshlrev_b32_e32 v19, 16, v209
	v_lshlrev_b32_e32 v18, 16, v208
	v_sub_f32_e32 v13, v16, v62
	v_pk_mul_f32 v[14:15], v[14:15], v[18:19]
	s_waitcnt vmcnt(12)
	v_lshlrev_b32_e32 v19, 16, v211
	v_lshlrev_b32_e32 v18, 16, v210
	v_mul_f32_e32 v13, 0x3fb8aa3b, v13
	v_pk_mul_f32 v[20:21], v[20:21], v[18:19]
	v_exp_f32_e32 v18, v13
	v_sub_f32_e32 v13, v16, v63
	v_mul_f32_e32 v13, 0x3fb8aa3b, v13
	v_exp_f32_e32 v19, v13
	v_sub_f32_e32 v13, v16, v64
	v_mul_f32_e32 v13, 0x3fb8aa3b, v13
	v_exp_f32_e32 v24, v13
	v_sub_f32_e32 v13, v16, v65
	v_mul_f32_e32 v13, 0x3fb8aa3b, v13
	v_exp_f32_e32 v25, v13
	s_waitcnt vmcnt(10)
	v_lshlrev_b32_e32 v23, 16, v213
	v_lshlrev_b32_e32 v22, 16, v212
	v_pk_mul_f32 v[22:23], v[18:19], v[22:23]
	s_waitcnt vmcnt(8)
	v_lshlrev_b32_e32 v19, 16, v215
	v_lshlrev_b32_e32 v18, 16, v214
	v_pk_mul_f32 v[24:25], v[24:25], v[18:19]
	v_cvt_pk_bf16_f32 v18, v14, v15
	v_cvt_pk_bf16_f32 v19, v20, v21
	v_cvt_pk_bf16_f32 v20, v22, v23
	v_cvt_pk_bf16_f32 v21, v24, v25
	v_sub_f32_e32 v13, v16, v68
	ds_write_b128 v37, v[18:21] offset:32
	v_mul_f32_e32 v13, 0x3fb8aa3b, v13
	s_waitcnt vmcnt(6)
	v_lshlrev_b32_e32 v19, 16, v217
	v_sub_f32_e32 v2, v16, v70
	v_exp_f32_e32 v14, v13
	v_sub_f32_e32 v13, v16, v69
	v_mul_f32_e32 v2, 0x3fb8aa3b, v2
	v_mul_f32_e32 v13, 0x3fb8aa3b, v13
	v_exp_f32_e32 v20, v2
	v_sub_f32_e32 v2, v16, v71
	v_exp_f32_e32 v15, v13
	v_mul_f32_e32 v2, 0x3fb8aa3b, v2
	v_exp_f32_e32 v21, v2
	v_lshlrev_b32_e32 v18, 16, v216
	v_sub_f32_e32 v2, v16, v72
	v_pk_mul_f32 v[14:15], v[14:15], v[18:19]
	s_waitcnt vmcnt(4)
	v_lshlrev_b32_e32 v19, 16, v219
	v_lshlrev_b32_e32 v18, 16, v218
	v_mul_f32_e32 v2, 0x3fb8aa3b, v2
	v_pk_mul_f32 v[20:21], v[20:21], v[18:19]
	v_exp_f32_e32 v18, v2
	v_sub_f32_e32 v2, v16, v73
	v_mul_f32_e32 v2, 0x3fb8aa3b, v2
	v_exp_f32_e32 v19, v2
	v_sub_f32_e32 v2, v16, v74
	v_mul_f32_e32 v2, 0x3fb8aa3b, v2
	v_exp_f32_e32 v24, v2
	v_sub_f32_e32 v2, v16, v75
	v_mul_f32_e32 v2, 0x3fb8aa3b, v2
	v_exp_f32_e32 v25, v2
	s_waitcnt vmcnt(2)
	v_lshlrev_b32_e32 v23, 16, v221
	v_lshlrev_b32_e32 v22, 16, v220
	v_pk_mul_f32 v[22:23], v[18:19], v[22:23]
	s_waitcnt vmcnt(0)
	v_lshlrev_b32_e32 v19, 16, v223
	v_lshlrev_b32_e32 v18, 16, v222
	v_pk_mul_f32 v[24:25], v[24:25], v[18:19]
	v_cvt_pk_bf16_f32 v18, v14, v15
	v_cvt_pk_bf16_f32 v19, v20, v21
	v_cvt_pk_bf16_f32 v20, v22, v23
	v_cvt_pk_bf16_f32 v21, v24, v25
	ds_write_b128 v37, v[18:21] offset:48
	s_and_saveexec_b64 s[0:1], vcc
	s_cbranch_execz .LBB0_340
	v_mul_f32_e32 v2, 0x3fb8aa3b, v16
	v_exp_f32_e32 v2, v2
	v_add_u32_e32 v14, s3, v32
	v_ashrrev_i32_e32 v15, 31, v14
	v_lshl_add_u64 v[14:15], v[14:15], 2, s[16:17]
	global_store_dword v[14:15], v2, off
	s_branch .LBB0_340
